# v25 + GEMM K-loop split barrier: all LDS reads in first half, free-barrier mid K-tile, DMA for K-tile kt+2 issued in 2nd half (1.45 K-tiles in flight)
# baseline (speedup 1.0000x reference)
.LBB0_203:
	s_add_u32 s52, s4, s6
	s_addc_u32 s4, s5, s7
	s_and_b32 s53, s4, 0xffff
	s_mul_hi_i32 s4, s14, s46
	s_mul_i32 s14, s14, s46
	s_add_u32 s56, s2, s14
	s_addc_u32 s2, s3, s4
	s_and_b32 s57, s2, 0xffff
	s_lshr_b32 s2, s0, 1
	s_lshr_b32 s47, s1, 6
	s_lshl_b32 s3, s1, 1
	s_and_b32 s2, s2, 0x1ffff80
	s_and_b32 s0, s0, 0xc0
	v_bfe_u32 v3, v0, 4, 2
	v_bfe_u32 v4, v0, 3, 3
	s_add_u32 s24, s26, 0x11884000
	v_mul_u32_u24_e32 v4, s3, v4
	v_bitop3_b32 v6, v3, v0, 7 bitop3:0x78
	s_addc_u32 s25, s27, 0
	s_lshl_b32 s76, s12, 12
	s_mov_b32 s58, s54
	s_mov_b32 s59, s55
	v_and_b32_e32 v5, 7, v0
	v_lshl_or_b32 v227, v6, 4, v4
	s_mul_i32 s96, s13, s3
	s_mov_b32 s32, 1
	s_mov_b32 m0, s76
	s_add_i32 s97, s76, 0x8000
	v_bitop3_b32 v5, v3, v5, 4 bitop3:0x36
	s_barrier
	s_mul_i32 s5, s8, s3
	buffer_load_dwordx4 v227, s[56:59], s96 offen lds
	s_mov_b32 m0, s97
	s_lshl_b32 s16, s1, 4
	s_or_b32 s94, s76, 0x400
	v_and_b32_e32 v2, 15, v0
	v_lshl_or_b32 v229, v5, 4, v4
	buffer_load_dwordx4 v227, s[52:55], s5 offen lds
	s_add_i32 s12, s96, s16
	s_mov_b32 m0, s94
	s_add_i32 s95, s76, 0x8400
	v_or_b32_e32 v5, s2, v2
	s_add_i32 s2, s5, s16
	buffer_load_dwordx4 v229, s[56:59], s12 offen lds
	s_mov_b32 m0, s95
	s_or_b32 s87, s76, 0x800
	buffer_load_dwordx4 v229, s[52:55], s2 offen lds
	s_add_i32 s86, s12, s16
	s_mov_b32 m0, s87
	s_add_i32 s20, s76, 0x8800
	s_add_i32 s2, s2, s16
	buffer_load_dwordx4 v227, s[56:59], s86 offen lds
	s_mov_b32 m0, s20
	s_or_b32 s22, s76, 0xc00
	buffer_load_dwordx4 v227, s[52:55], s2 offen lds
	s_add_i32 s21, s86, s16
	s_mov_b32 m0, s22
	s_add_i32 s23, s76, 0x8c00
	s_add_i32 s2, s2, s16
	buffer_load_dwordx4 v229, s[56:59], s21 offen lds
	s_mov_b32 m0, s23
	v_writelane_b32 v254, s3, 42
	buffer_load_dwordx4 v229, s[52:55], s2 offen lds
	s_add_u32 s2, s26, 0x1000000
	s_addc_u32 s3, s27, 0
	v_writelane_b32 v254, s2, 43
	v_or_b32_e32 v2, s0, v2
	v_lshrrev_b32_e32 v4, 1, v0
	v_writelane_b32 v254, s3, 44
	s_add_u32 s2, s26, 0x8880000
	s_addc_u32 s3, s27, 0
	v_writelane_b32 v254, s2, 45
	v_bfe_u32 v0, v0, 1, 3
	v_bitop3_b32 v4, v3, v4, 7 bitop3:0x78
	v_writelane_b32 v254, s3, 46
	s_add_u32 s2, s26, 0xe00000
	s_addc_u32 s3, s27, 0
	v_writelane_b32 v254, s2, 47
	v_bitop3_b32 v0, v3, v0, 4 bitop3:0x36
	v_lshlrev_b32_e32 v2, 7, v2
	v_writelane_b32 v254, s3, 48
	s_add_u32 s2, s26, 0x800000
	s_addc_u32 s3, s27, 0
	v_writelane_b32 v254, s2, 49
	v_lshlrev_b32_e32 v5, 7, v5
	v_lshlrev_b32_e32 v4, 4, v4
	v_writelane_b32 v254, s3, 50
	s_add_u32 s2, s26, 0xd880000
	s_addc_u32 s3, s27, 0
	v_writelane_b32 v254, s2, 51
	v_lshlrev_b32_e32 v0, 4, v0
	v_or_b32_e32 v3, 0x8000, v2
	v_writelane_b32 v254, s3, 52
	s_add_u32 s2, s26, 0x600000
	s_addc_u32 s3, s27, 0
	v_writelane_b32 v254, s2, 53
	s_add_u32 s0, s26, 0x5880000
	v_or_b32_e32 v231, v5, v4
	v_writelane_b32 v254, s3, 54
	v_writelane_b32 v254, s0, 55
	s_addc_u32 s0, s27, 0
	v_writelane_b32 v254, s0, 56
	s_mov_b32 s0, 0x500000
	v_readlane_b32 s6, v254, 19
	v_readlane_b32 s7, v254, 20
	s_and_b64 s[2:3], s[6:7], exec
	s_cselect_b32 s0, s0, 0x400000
	s_add_u32 s2, s26, s0
	s_addc_u32 s3, s27, 0
	v_writelane_b32 v254, s2, 57
	v_or_b32_e32 v233, v5, v0
	v_or_b32_e32 v235, v3, v4
	v_writelane_b32 v254, s3, 58
	s_and_b64 s[2:3], s[6:7], exec
	s_cselect_b32 s0, 10, 8
	s_add_u32 s2, s26, 0x7880000
	v_writelane_b32 v254, s0, 59
	s_addc_u32 s3, s27, 0
	v_writelane_b32 v254, s2, 60
	v_or_b32_e32 v237, v3, v0
	v_or_b32_e32 v239, v2, v4
	v_writelane_b32 v254, s3, 61
	s_add_u32 s2, s26, 0x1b00000
	s_addc_u32 s3, s27, 0
	v_writelane_b32 v254, s2, 62
	s_cmp_eq_u32 s10, 0
	s_cselect_b32 s0, 0, 0xb00
	v_writelane_b32 v254, s3, 63
	s_add_i32 s0, s0, s11
	v_readlane_b32 s2, v254, 22
	v_readlane_b32 s3, v254, 23
	s_mov_b32 s4, s2
	s_mul_i32 s2, s2, 3
	s_ashr_i32 s3, s2, 31
	s_lshl_b64 s[2:3], s[2:3], 20
	s_add_u32 s8, s24, s2
	s_addc_u32 s9, s25, s3
	s_add_u32 s2, s8, 0x200000
	v_writelane_b32 v255, s0, 0
	s_addc_u32 s3, s9, 0
	v_writelane_b32 v255, s2, 1
	v_readlane_b32 s58, v254, 40
	v_or_b32_e32 v241, v2, v0
	v_writelane_b32 v255, s3, 2
	s_add_u32 s2, s26, 0x6880000
	s_addc_u32 s3, s27, 0
	v_writelane_b32 v255, s2, 3
	s_mov_b64 s[90:91], s[54:55]
	s_mov_b64 s[92:93], s[54:55]
	v_writelane_b32 v255, s3, 4
	s_add_u32 s2, s8, 0x100000
	s_addc_u32 s3, s9, 0
	v_writelane_b32 v255, s2, 5
	s_add_u32 s0, s26, 0x5080000
	v_readlane_b32 s59, v254, 41
	v_writelane_b32 v255, s3, 6
	v_writelane_b32 v255, s0, 7
	s_addc_u32 s0, s27, 0
	v_writelane_b32 v255, s0, 8
	s_add_u32 s0, s26, 0x4880000
	v_writelane_b32 v255, s0, 9
	s_addc_u32 s0, s27, 0
	v_writelane_b32 v255, s0, 10
	s_and_b64 s[2:3], s[6:7], exec
	s_mov_b32 s0, 0x200000
	s_cselect_b32 s80, s0, 0x400000
	v_writelane_b32 v255, s80, 11
	s_add_u32 s2, s26, 0xb880000
	s_addc_u32 s3, s27, 0
	v_writelane_b32 v255, s81, 12
	v_writelane_b32 v255, s2, 13
	s_mul_i32 s0, s1, 48
	s_waitcnt vmcnt(0)
	v_writelane_b32 v255, s3, 14
	s_lshl_b32 s2, s4, 5
	s_ashr_i32 s3, s2, 31
	s_add_u32 s6, s8, 0x300000
	v_writelane_b32 v255, s8, 15
	s_addc_u32 s7, s9, 0
	s_lshl_b32 s10, s1, 5
	v_writelane_b32 v255, s9, 16
	v_writelane_b32 v255, s6, 17
	s_add_i32 s9, s76, 0x10000
	s_add_i32 s72, s76, 0x18000
	v_writelane_b32 v255, s7, 18
	v_writelane_b32 v255, s0, 19
	s_lshl_b64 s[0:1], s[2:3], 2
	v_writelane_b32 v255, s0, 20
	s_add_i32 s13, s76, 0x10400
	s_add_i32 s85, s76, 0x18400
	s_add_i32 s11, s76, 0x10800
	s_add_i32 s84, s76, 0x18800
	s_add_i32 s8, s76, 0x10c00
	s_add_i32 s34, s76, 0x18c00
	v_writelane_b32 v255, s1, 21
	v_readlane_b32 s4, v253, 0
	s_barrier
	s_branch .LBB0_206

.LBB0_247:
	v_readlane_b32 s3, v255, 19
	v_mov_b32_e32 v2, 0
	s_add_i32 s2, s10, s1
	s_add_i32 s3, s3, s1
	s_add_i32 s14, s16, s1
	s_movk_i32 s15, 0x100
	s_mov_b32 s28, 2
	v_mov_b32_e32 v3, v2
	v_mov_b32_e32 v4, v2
	v_mov_b32_e32 v5, v2
	v_mov_b32_e32 v6, v2
	v_mov_b32_e32 v7, v2
	v_mov_b32_e32 v8, v2
	v_mov_b32_e32 v9, v2
	v_mov_b32_e32 v10, v2
	v_mov_b32_e32 v11, v2
	v_mov_b32_e32 v12, v2
	v_mov_b32_e32 v13, v2
	v_mov_b32_e32 v14, v2
	v_mov_b32_e32 v15, v2
	v_mov_b32_e32 v16, v2
	v_mov_b32_e32 v17, v2
	v_mov_b32_e32 v18, v2
	v_mov_b32_e32 v19, v2
	v_mov_b32_e32 v20, v2
	v_mov_b32_e32 v21, v2
	v_mov_b32_e32 v22, v2
	v_mov_b32_e32 v23, v2
	v_mov_b32_e32 v24, v2
	v_mov_b32_e32 v25, v2
	v_mov_b32_e32 v26, v2
	v_mov_b32_e32 v27, v2
	v_mov_b32_e32 v28, v2
	v_mov_b32_e32 v29, v2
	v_mov_b32_e32 v30, v2
	v_mov_b32_e32 v31, v2
	v_mov_b32_e32 v32, v2
	v_mov_b32_e32 v33, v2
	v_mov_b32_e32 v34, v2
	v_mov_b32_e32 v35, v2
	v_mov_b32_e32 v36, v2
	v_mov_b32_e32 v37, v2
	v_mov_b32_e32 v38, v2
	v_mov_b32_e32 v39, v2
	v_mov_b32_e32 v40, v2
	v_mov_b32_e32 v41, v2
	v_mov_b32_e32 v42, v2
	v_mov_b32_e32 v43, v2
	v_mov_b32_e32 v44, v2
	v_mov_b32_e32 v45, v2
	v_mov_b32_e32 v46, v2
	v_mov_b32_e32 v47, v2
	v_mov_b32_e32 v48, v2
	v_mov_b32_e32 v49, v2
	v_mov_b32_e32 v50, v2
	v_mov_b32_e32 v51, v2
	v_mov_b32_e32 v52, v2
	v_mov_b32_e32 v53, v2
	v_mov_b32_e32 v54, v2
	v_mov_b32_e32 v55, v2
	v_mov_b32_e32 v56, v2
	v_mov_b32_e32 v57, v2
	v_mov_b32_e32 v58, v2
	v_mov_b32_e32 v59, v2
	v_mov_b32_e32 v60, v2
	v_mov_b32_e32 v61, v2
	v_mov_b32_e32 v62, v2
	v_mov_b32_e32 v63, v2
	v_mov_b32_e32 v64, v2
	v_mov_b32_e32 v65, v2
	v_mov_b32_e32 v66, v2
	v_mov_b32_e32 v67, v2
	v_mov_b32_e32 v68, v2
	v_mov_b32_e32 v69, v2
	v_mov_b32_e32 v70, v2
	v_mov_b32_e32 v71, v2
	v_mov_b32_e32 v72, v2
	v_mov_b32_e32 v73, v2
	v_mov_b32_e32 v74, v2
	v_mov_b32_e32 v75, v2
	v_mov_b32_e32 v76, v2
	v_mov_b32_e32 v77, v2
	v_mov_b32_e32 v78, v2
	v_mov_b32_e32 v79, v2
	v_mov_b32_e32 v80, v2
	v_mov_b32_e32 v81, v2
	v_mov_b32_e32 v82, v2
	v_mov_b32_e32 v83, v2
	v_mov_b32_e32 v84, v2
	v_mov_b32_e32 v85, v2
	v_mov_b32_e32 v86, v2
	v_mov_b32_e32 v87, v2
	v_mov_b32_e32 v88, v2
	v_mov_b32_e32 v89, v2
	v_mov_b32_e32 v90, v2
	v_mov_b32_e32 v91, v2
	v_mov_b32_e32 v92, v2
	v_mov_b32_e32 v93, v2
	v_mov_b32_e32 v94, v2
	v_mov_b32_e32 v95, v2
	v_mov_b32_e32 v96, v2
	v_mov_b32_e32 v97, v2
	v_mov_b32_e32 v98, v2
	v_mov_b32_e32 v99, v2
	v_mov_b32_e32 v100, v2
	v_mov_b32_e32 v101, v2
	v_mov_b32_e32 v102, v2
	v_mov_b32_e32 v103, v2
	v_mov_b32_e32 v104, v2
	v_mov_b32_e32 v105, v2
	v_mov_b32_e32 v106, v2
	v_mov_b32_e32 v107, v2
	v_mov_b32_e32 v108, v2
	v_mov_b32_e32 v109, v2
	v_mov_b32_e32 v110, v2
	v_mov_b32_e32 v111, v2
	v_mov_b32_e32 v112, v2
	v_mov_b32_e32 v113, v2
	v_mov_b32_e32 v114, v2
	v_mov_b32_e32 v115, v2
	v_mov_b32_e32 v116, v2
	v_mov_b32_e32 v117, v2
	v_mov_b32_e32 v118, v2
	v_mov_b32_e32 v119, v2
	v_mov_b32_e32 v120, v2
	v_mov_b32_e32 v121, v2
	v_mov_b32_e32 v122, v2
	v_mov_b32_e32 v123, v2
	v_mov_b32_e32 v124, v2
	v_mov_b32_e32 v125, v2
	v_mov_b32_e32 v126, v2
	v_mov_b32_e32 v127, v2
	v_mov_b32_e32 v128, v2
	v_mov_b32_e32 v129, v2
	v_add_u32_e32 v235, 0x10000, v231
	v_add_u32_e32 v237, 0x10000, v233
	v_add_u32_e32 v226, 0x10000, v239
	v_add_u32_e32 v228, 0x10000, v241
	s_cmp_eq_u32 s32, 1
	s_cbranch_scc0 .Lg2_notfirst
	s_mov_b32 s32, 0
	s_mov_b32 m0, s9
	s_add_i32 s39, s96, 0x80
	buffer_load_dwordx4 v227, s[40:43], s39 offen lds
	s_mov_b32 m0, s72
	s_add_i32 s39, s1, 0x80
	buffer_load_dwordx4 v227, s[60:63], s39 offen lds
	s_mov_b32 m0, s13
	s_add_i32 s39, s12, 0x80
	buffer_load_dwordx4 v229, s[40:43], s39 offen lds
	s_mov_b32 m0, s85
	s_add_i32 s39, s14, 0x80
	buffer_load_dwordx4 v229, s[60:63], s39 offen lds
	s_mov_b32 m0, s11
	s_add_i32 s39, s86, 0x80
	buffer_load_dwordx4 v227, s[40:43], s39 offen lds
	s_mov_b32 m0, s84
	s_add_i32 s39, s2, 0x80
	buffer_load_dwordx4 v227, s[60:63], s39 offen lds
	s_mov_b32 m0, s8
	s_add_i32 s39, s21, 0x80
	buffer_load_dwordx4 v229, s[40:43], s39 offen lds
	s_mov_b32 m0, s34
	s_add_i32 s39, s3, 0x80
	buffer_load_dwordx4 v229, s[60:63], s39 offen lds
.Lg2_notfirst:
	ds_read_b128 v[130:133], v239 offset:32768
	ds_read_b128 v[134:137], v239 offset:34816
	ds_read_b128 v[138:141], v239 offset:36864
	ds_read_b128 v[142:145], v239 offset:38912
	ds_read_b128 v[146:149], v231
	ds_read_b128 v[150:153], v231 offset:2048
	ds_read_b128 v[154:157], v231 offset:4096
	ds_read_b128 v[158:161], v231 offset:6144
	ds_read_b128 v[162:165], v231 offset:8192
	ds_read_b128 v[166:169], v231 offset:10240
	ds_read_b128 v[170:173], v231 offset:12288
	ds_read_b128 v[174:177], v231 offset:14336
	s_waitcnt lgkmcnt(0)
	ds_read_b128 v[178:181], v241 offset:32768
	ds_read_b128 v[182:185], v241 offset:34816
	ds_read_b128 v[186:189], v241 offset:36864
	ds_read_b128 v[190:193], v241 offset:38912
	ds_read_b128 v[194:197], v233
	ds_read_b128 v[198:201], v233 offset:2048
	ds_read_b128 v[202:205], v233 offset:4096
	ds_read_b128 v[206:209], v233 offset:6144
	ds_read_b128 v[210:213], v233 offset:8192
	ds_read_b128 v[214:217], v233 offset:10240
	ds_read_b128 v[218:221], v233 offset:12288
	ds_read_b128 v[222:225], v233 offset:14336
	s_cmp_lt_u32 s28, s47
	s_cselect_b64 s[30:31], -1, 0
	s_cmp_ge_u32 s28, s47
	s_cselect_b64 s[6:7], -1, 0
	s_or_b64 s[36:37], s[26:27], s[30:31]
	s_and_b64 s[30:31], s[30:31], exec
	s_cselect_b32 s30, s1, s5
	s_cselect_b32 s29, s15, 0
	s_cselect_b32 s67, s43, s93
	s_cselect_b32 s66, s42, s92
	s_cselect_b32 s65, s41, s57
	s_cselect_b32 s64, s40, s56
	s_cselect_b32 s71, s63, s91
	s_cselect_b32 s70, s62, s90
	s_cselect_b32 s69, s61, s53
	s_cselect_b32 s68, s60, s52
	s_add_i32 s30, s29, s30
	s_and_b32 s66, s66, s36
	s_and_b32 s70, s70, s36
	s_branch .Lg2_q_even
.Lg2_top:
	s_cmp_lt_u32 s28, s47
	s_cselect_b64 s[30:31], -1, 0
	s_cmp_ge_u32 s28, s47
	s_cselect_b64 s[6:7], -1, 0
	s_or_b64 s[36:37], s[26:27], s[30:31]
	s_and_b64 s[30:31], s[30:31], exec
	s_cselect_b32 s30, s1, s5
	s_cselect_b32 s29, s15, 0
	s_cselect_b32 s67, s43, s93
	s_cselect_b32 s66, s42, s92
	s_cselect_b32 s65, s41, s57
	s_cselect_b32 s64, s40, s56
	s_cselect_b32 s71, s63, s91
	s_cselect_b32 s70, s62, s90
	s_cselect_b32 s69, s61, s53
	s_cselect_b32 s68, s60, s52
	s_add_i32 s30, s29, s30
	s_and_b32 s66, s66, s36
	s_and_b32 s70, s70, s36
	v_mfma_f32_16x16x32_bf16 v[126:129], v[178:181], v[194:197], v[126:129]
	ds_read_b128 v[130:133], v239 offset:32768
	v_mfma_f32_16x16x32_bf16 v[122:125], v[182:185], v[194:197], v[122:125]
	ds_read_b128 v[134:137], v239 offset:34816
	v_mfma_f32_16x16x32_bf16 v[118:121], v[186:189], v[194:197], v[118:121]
	ds_read_b128 v[138:141], v239 offset:36864
	v_mfma_f32_16x16x32_bf16 v[114:117], v[190:193], v[194:197], v[114:117]
	ds_read_b128 v[142:145], v239 offset:38912
	v_mfma_f32_16x16x32_bf16 v[110:113], v[178:181], v[198:201], v[110:113]
	ds_read_b128 v[146:149], v231
	v_mfma_f32_16x16x32_bf16 v[106:109], v[182:185], v[198:201], v[106:109]
	ds_read_b128 v[150:153], v231 offset:2048
	v_mfma_f32_16x16x32_bf16 v[102:105], v[186:189], v[198:201], v[102:105]
	ds_read_b128 v[154:157], v231 offset:4096
	v_mfma_f32_16x16x32_bf16 v[98:101], v[190:193], v[198:201], v[98:101]
	ds_read_b128 v[158:161], v231 offset:6144
	v_mfma_f32_16x16x32_bf16 v[94:97], v[178:181], v[202:205], v[94:97]
	ds_read_b128 v[162:165], v231 offset:8192
	v_mfma_f32_16x16x32_bf16 v[90:93], v[182:185], v[202:205], v[90:93]
	ds_read_b128 v[166:169], v231 offset:10240
	v_mfma_f32_16x16x32_bf16 v[86:89], v[186:189], v[202:205], v[86:89]
	ds_read_b128 v[170:173], v231 offset:12288
	v_mfma_f32_16x16x32_bf16 v[82:85], v[190:193], v[202:205], v[82:85]
	ds_read_b128 v[174:177], v231 offset:14336
	v_mfma_f32_16x16x32_bf16 v[78:81], v[178:181], v[206:209], v[78:81]
	ds_read_b128 v[194:197], v233
	v_mfma_f32_16x16x32_bf16 v[74:77], v[182:185], v[206:209], v[74:77]
	ds_read_b128 v[198:201], v233 offset:2048
	v_mfma_f32_16x16x32_bf16 v[70:73], v[186:189], v[206:209], v[70:73]
	ds_read_b128 v[202:205], v233 offset:4096
	v_mfma_f32_16x16x32_bf16 v[66:69], v[190:193], v[206:209], v[66:69]
	ds_read_b128 v[206:209], v233 offset:6144
	v_mfma_f32_16x16x32_bf16 v[62:65], v[178:181], v[210:213], v[62:65]
	v_mfma_f32_16x16x32_bf16 v[58:61], v[182:185], v[210:213], v[58:61]
	v_mfma_f32_16x16x32_bf16 v[54:57], v[186:189], v[210:213], v[54:57]
	v_mfma_f32_16x16x32_bf16 v[50:53], v[190:193], v[210:213], v[50:53]
	ds_read_b128 v[210:213], v233 offset:8192
	v_mfma_f32_16x16x32_bf16 v[46:49], v[178:181], v[214:217], v[46:49]
	v_mfma_f32_16x16x32_bf16 v[42:45], v[182:185], v[214:217], v[42:45]
	v_mfma_f32_16x16x32_bf16 v[38:41], v[186:189], v[214:217], v[38:41]
	v_mfma_f32_16x16x32_bf16 v[34:37], v[190:193], v[214:217], v[34:37]
	ds_read_b128 v[214:217], v233 offset:10240
	v_mfma_f32_16x16x32_bf16 v[30:33], v[178:181], v[218:221], v[30:33]
	v_mfma_f32_16x16x32_bf16 v[26:29], v[182:185], v[218:221], v[26:29]
	v_mfma_f32_16x16x32_bf16 v[22:25], v[186:189], v[218:221], v[22:25]
	v_mfma_f32_16x16x32_bf16 v[18:21], v[190:193], v[218:221], v[18:21]
	ds_read_b128 v[218:221], v233 offset:12288
	v_mfma_f32_16x16x32_bf16 v[14:17], v[178:181], v[222:225], v[14:17]
	v_mfma_f32_16x16x32_bf16 v[10:13], v[182:185], v[222:225], v[10:13]
	v_mfma_f32_16x16x32_bf16 v[6:9], v[186:189], v[222:225], v[6:9]
	v_mfma_f32_16x16x32_bf16 v[2:5], v[190:193], v[222:225], v[2:5]
	ds_read_b128 v[222:225], v233 offset:14336
	ds_read_b128 v[178:181], v241 offset:32768
	ds_read_b128 v[182:185], v241 offset:34816
	ds_read_b128 v[186:189], v241 offset:36864
	ds_read_b128 v[190:193], v241 offset:38912
	s_waitcnt lgkmcnt(5)
.Lg2_q_even:
	v_mfma_f32_16x16x32_bf16 v[126:129], v[130:133], v[146:149], v[126:129]
	v_mfma_f32_16x16x32_bf16 v[122:125], v[134:137], v[146:149], v[122:125]
	v_mfma_f32_16x16x32_bf16 v[118:121], v[138:141], v[146:149], v[118:121]
	v_mfma_f32_16x16x32_bf16 v[114:117], v[142:145], v[146:149], v[114:117]
	v_mfma_f32_16x16x32_bf16 v[110:113], v[130:133], v[150:153], v[110:113]
	v_mfma_f32_16x16x32_bf16 v[106:109], v[134:137], v[150:153], v[106:109]
	v_mfma_f32_16x16x32_bf16 v[102:105], v[138:141], v[150:153], v[102:105]
	v_mfma_f32_16x16x32_bf16 v[98:101], v[142:145], v[150:153], v[98:101]
	s_waitcnt lgkmcnt(0)
	s_barrier
	v_mfma_f32_16x16x32_bf16 v[94:97], v[130:133], v[154:157], v[94:97]
	s_mov_b32 m0, s76
	s_add_i32 s39, s29, s96
	buffer_load_dwordx4 v227, s[64:67], s39 offen lds
	v_mfma_f32_16x16x32_bf16 v[90:93], v[134:137], v[154:157], v[90:93]
	v_mfma_f32_16x16x32_bf16 v[86:89], v[138:141], v[154:157], v[86:89]
	v_mfma_f32_16x16x32_bf16 v[82:85], v[142:145], v[154:157], v[82:85]
	s_mov_b32 m0, s97
	s_nop 0
	buffer_load_dwordx4 v227, s[68:71], s30 offen lds
	v_mfma_f32_16x16x32_bf16 v[78:81], v[130:133], v[158:161], v[78:81]
	v_mfma_f32_16x16x32_bf16 v[74:77], v[134:137], v[158:161], v[74:77]
	v_mfma_f32_16x16x32_bf16 v[70:73], v[138:141], v[158:161], v[70:73]
	s_mov_b32 m0, s94
	s_add_i32 s39, s29, s12
	buffer_load_dwordx4 v229, s[64:67], s39 offen lds
	v_mfma_f32_16x16x32_bf16 v[66:69], v[142:145], v[158:161], v[66:69]
	v_mfma_f32_16x16x32_bf16 v[62:65], v[130:133], v[162:165], v[62:65]
	v_mfma_f32_16x16x32_bf16 v[58:61], v[134:137], v[162:165], v[58:61]
	s_mov_b32 m0, s95
	s_add_i32 s39, s30, s16
	buffer_load_dwordx4 v229, s[68:71], s39 offen lds
	v_mfma_f32_16x16x32_bf16 v[54:57], v[138:141], v[162:165], v[54:57]
	v_mfma_f32_16x16x32_bf16 v[50:53], v[142:145], v[162:165], v[50:53]
	v_mfma_f32_16x16x32_bf16 v[46:49], v[130:133], v[166:169], v[46:49]
	s_mov_b32 m0, s87
	s_add_i32 s39, s29, s86
	buffer_load_dwordx4 v227, s[64:67], s39 offen lds
	v_mfma_f32_16x16x32_bf16 v[42:45], v[134:137], v[166:169], v[42:45]
	v_mfma_f32_16x16x32_bf16 v[38:41], v[138:141], v[166:169], v[38:41]
	v_mfma_f32_16x16x32_bf16 v[34:37], v[142:145], v[166:169], v[34:37]
	s_mov_b32 m0, s20
	s_add_i32 s39, s30, s10
	buffer_load_dwordx4 v227, s[68:71], s39 offen lds
	v_mfma_f32_16x16x32_bf16 v[30:33], v[130:133], v[170:173], v[30:33]
	v_mfma_f32_16x16x32_bf16 v[26:29], v[134:137], v[170:173], v[26:29]
	v_mfma_f32_16x16x32_bf16 v[22:25], v[138:141], v[170:173], v[22:25]
	s_mov_b32 m0, s22
	s_add_i32 s39, s29, s21
	buffer_load_dwordx4 v229, s[64:67], s39 offen lds
	v_mfma_f32_16x16x32_bf16 v[18:21], v[142:145], v[170:173], v[18:21]
	v_mfma_f32_16x16x32_bf16 v[14:17], v[130:133], v[174:177], v[14:17]
	v_mfma_f32_16x16x32_bf16 v[10:13], v[134:137], v[174:177], v[10:13]
	s_mov_b32 m0, s23
	s_add_i32 s37, s30, s10
	s_add_i32 s39, s37, s16
	buffer_load_dwordx4 v229, s[68:71], s39 offen lds
	v_mfma_f32_16x16x32_bf16 v[6:9], v[138:141], v[174:177], v[6:9]
	v_mfma_f32_16x16x32_bf16 v[2:5], v[142:145], v[174:177], v[2:5]
	s_waitcnt vmcnt(8)
	s_barrier
	v_mfma_f32_16x16x32_bf16 v[126:129], v[178:181], v[194:197], v[126:129]
	ds_read_b128 v[130:133], v226 offset:32768
	v_mfma_f32_16x16x32_bf16 v[122:125], v[182:185], v[194:197], v[122:125]
	ds_read_b128 v[134:137], v226 offset:34816
	v_mfma_f32_16x16x32_bf16 v[118:121], v[186:189], v[194:197], v[118:121]
	ds_read_b128 v[138:141], v226 offset:36864
	v_mfma_f32_16x16x32_bf16 v[114:117], v[190:193], v[194:197], v[114:117]
	ds_read_b128 v[142:145], v226 offset:38912
	v_mfma_f32_16x16x32_bf16 v[110:113], v[178:181], v[198:201], v[110:113]
	ds_read_b128 v[146:149], v235
	v_mfma_f32_16x16x32_bf16 v[106:109], v[182:185], v[198:201], v[106:109]
	ds_read_b128 v[150:153], v235 offset:2048
	v_mfma_f32_16x16x32_bf16 v[102:105], v[186:189], v[198:201], v[102:105]
	ds_read_b128 v[154:157], v235 offset:4096
	v_mfma_f32_16x16x32_bf16 v[98:101], v[190:193], v[198:201], v[98:101]
	ds_read_b128 v[158:161], v235 offset:6144
	v_mfma_f32_16x16x32_bf16 v[94:97], v[178:181], v[202:205], v[94:97]
	ds_read_b128 v[162:165], v235 offset:8192
	v_mfma_f32_16x16x32_bf16 v[90:93], v[182:185], v[202:205], v[90:93]
	ds_read_b128 v[166:169], v235 offset:10240
	v_mfma_f32_16x16x32_bf16 v[86:89], v[186:189], v[202:205], v[86:89]
	ds_read_b128 v[170:173], v235 offset:12288
	v_mfma_f32_16x16x32_bf16 v[82:85], v[190:193], v[202:205], v[82:85]
	ds_read_b128 v[174:177], v235 offset:14336
	v_mfma_f32_16x16x32_bf16 v[78:81], v[178:181], v[206:209], v[78:81]
	ds_read_b128 v[194:197], v237
	v_mfma_f32_16x16x32_bf16 v[74:77], v[182:185], v[206:209], v[74:77]
	ds_read_b128 v[198:201], v237 offset:2048
	v_mfma_f32_16x16x32_bf16 v[70:73], v[186:189], v[206:209], v[70:73]
	ds_read_b128 v[202:205], v237 offset:4096
	v_mfma_f32_16x16x32_bf16 v[66:69], v[190:193], v[206:209], v[66:69]
	ds_read_b128 v[206:209], v237 offset:6144
	v_mfma_f32_16x16x32_bf16 v[62:65], v[178:181], v[210:213], v[62:65]
	v_mfma_f32_16x16x32_bf16 v[58:61], v[182:185], v[210:213], v[58:61]
	v_mfma_f32_16x16x32_bf16 v[54:57], v[186:189], v[210:213], v[54:57]
	v_mfma_f32_16x16x32_bf16 v[50:53], v[190:193], v[210:213], v[50:53]
	ds_read_b128 v[210:213], v237 offset:8192
	v_mfma_f32_16x16x32_bf16 v[46:49], v[178:181], v[214:217], v[46:49]
	v_mfma_f32_16x16x32_bf16 v[42:45], v[182:185], v[214:217], v[42:45]
	v_mfma_f32_16x16x32_bf16 v[38:41], v[186:189], v[214:217], v[38:41]
	v_mfma_f32_16x16x32_bf16 v[34:37], v[190:193], v[214:217], v[34:37]
	ds_read_b128 v[214:217], v237 offset:10240
	v_mfma_f32_16x16x32_bf16 v[30:33], v[178:181], v[218:221], v[30:33]
	v_mfma_f32_16x16x32_bf16 v[26:29], v[182:185], v[218:221], v[26:29]
	v_mfma_f32_16x16x32_bf16 v[22:25], v[186:189], v[218:221], v[22:25]
	v_mfma_f32_16x16x32_bf16 v[18:21], v[190:193], v[218:221], v[18:21]
	ds_read_b128 v[218:221], v237 offset:12288
	v_mfma_f32_16x16x32_bf16 v[14:17], v[178:181], v[222:225], v[14:17]
	v_mfma_f32_16x16x32_bf16 v[10:13], v[182:185], v[222:225], v[10:13]
	v_mfma_f32_16x16x32_bf16 v[6:9], v[186:189], v[222:225], v[6:9]
	v_mfma_f32_16x16x32_bf16 v[2:5], v[190:193], v[222:225], v[2:5]
	ds_read_b128 v[222:225], v237 offset:14336
	ds_read_b128 v[178:181], v228 offset:32768
	ds_read_b128 v[182:185], v228 offset:34816
	ds_read_b128 v[186:189], v228 offset:36864
	ds_read_b128 v[190:193], v228 offset:38912
	s_waitcnt lgkmcnt(5)
	v_mfma_f32_16x16x32_bf16 v[126:129], v[130:133], v[146:149], v[126:129]
	v_mfma_f32_16x16x32_bf16 v[122:125], v[134:137], v[146:149], v[122:125]
	v_mfma_f32_16x16x32_bf16 v[118:121], v[138:141], v[146:149], v[118:121]
	v_mfma_f32_16x16x32_bf16 v[114:117], v[142:145], v[146:149], v[114:117]
	v_mfma_f32_16x16x32_bf16 v[110:113], v[130:133], v[150:153], v[110:113]
	v_mfma_f32_16x16x32_bf16 v[106:109], v[134:137], v[150:153], v[106:109]
	v_mfma_f32_16x16x32_bf16 v[102:105], v[138:141], v[150:153], v[102:105]
	v_mfma_f32_16x16x32_bf16 v[98:101], v[142:145], v[150:153], v[98:101]
	s_waitcnt lgkmcnt(0)
	s_barrier
	v_mfma_f32_16x16x32_bf16 v[94:97], v[130:133], v[154:157], v[94:97]
	s_mov_b32 m0, s9
	s_add_i32 s39, s29, s96
	s_addk_i32 s39, 0x80
	buffer_load_dwordx4 v227, s[64:67], s39 offen lds
	v_mfma_f32_16x16x32_bf16 v[90:93], v[134:137], v[154:157], v[90:93]
	v_mfma_f32_16x16x32_bf16 v[86:89], v[138:141], v[154:157], v[86:89]
	v_mfma_f32_16x16x32_bf16 v[82:85], v[142:145], v[154:157], v[82:85]
	s_mov_b32 m0, s72
	s_add_i32 s39, s30, 0x80
	buffer_load_dwordx4 v227, s[68:71], s39 offen lds
	v_mfma_f32_16x16x32_bf16 v[78:81], v[130:133], v[158:161], v[78:81]
	v_mfma_f32_16x16x32_bf16 v[74:77], v[134:137], v[158:161], v[74:77]
	v_mfma_f32_16x16x32_bf16 v[70:73], v[138:141], v[158:161], v[70:73]
	s_mov_b32 m0, s13
	s_add_i32 s39, s29, s12
	s_addk_i32 s39, 0x80
	buffer_load_dwordx4 v229, s[64:67], s39 offen lds
	v_mfma_f32_16x16x32_bf16 v[66:69], v[142:145], v[158:161], v[66:69]
	v_mfma_f32_16x16x32_bf16 v[62:65], v[130:133], v[162:165], v[62:65]
	v_mfma_f32_16x16x32_bf16 v[58:61], v[134:137], v[162:165], v[58:61]
	s_mov_b32 m0, s85
	s_add_i32 s39, s30, s16
	s_addk_i32 s39, 0x80
	buffer_load_dwordx4 v229, s[68:71], s39 offen lds
	v_mfma_f32_16x16x32_bf16 v[54:57], v[138:141], v[162:165], v[54:57]
	v_mfma_f32_16x16x32_bf16 v[50:53], v[142:145], v[162:165], v[50:53]
	v_mfma_f32_16x16x32_bf16 v[46:49], v[130:133], v[166:169], v[46:49]
	s_mov_b32 m0, s11
	s_add_i32 s39, s29, s86
	s_addk_i32 s39, 0x80
	buffer_load_dwordx4 v227, s[64:67], s39 offen lds
	v_mfma_f32_16x16x32_bf16 v[42:45], v[134:137], v[166:169], v[42:45]
	v_mfma_f32_16x16x32_bf16 v[38:41], v[138:141], v[166:169], v[38:41]
	v_mfma_f32_16x16x32_bf16 v[34:37], v[142:145], v[166:169], v[34:37]
	s_mov_b32 m0, s84
	s_add_i32 s39, s30, s10
	s_addk_i32 s39, 0x80
	buffer_load_dwordx4 v227, s[68:71], s39 offen lds
	v_mfma_f32_16x16x32_bf16 v[30:33], v[130:133], v[170:173], v[30:33]
	v_mfma_f32_16x16x32_bf16 v[26:29], v[134:137], v[170:173], v[26:29]
	v_mfma_f32_16x16x32_bf16 v[22:25], v[138:141], v[170:173], v[22:25]
	s_mov_b32 m0, s8
	s_add_i32 s39, s29, s21
	s_addk_i32 s39, 0x80
	buffer_load_dwordx4 v229, s[64:67], s39 offen lds
	v_mfma_f32_16x16x32_bf16 v[18:21], v[142:145], v[170:173], v[18:21]
	v_mfma_f32_16x16x32_bf16 v[14:17], v[130:133], v[174:177], v[14:17]
	v_mfma_f32_16x16x32_bf16 v[10:13], v[134:137], v[174:177], v[10:13]
	s_mov_b32 m0, s34
	s_add_i32 s37, s30, s10
	s_add_i32 s39, s37, s16
	s_addk_i32 s39, 0x80
	buffer_load_dwordx4 v229, s[68:71], s39 offen lds
	v_mfma_f32_16x16x32_bf16 v[6:9], v[138:141], v[174:177], v[6:9]
	v_mfma_f32_16x16x32_bf16 v[2:5], v[142:145], v[174:177], v[2:5]
	s_addk_i32 s15, 0x100
	s_add_i32 s28, s28, 2
	s_and_b64 vcc, exec, s[6:7]
	s_waitcnt vmcnt(8)
	s_barrier
	s_cbranch_vccz .Lg2_top
	v_mov_b32_e32 v226, 0x8000
	v_mov_b32_e32 v228, 0x8004
